# per-XCD flash queues, order within a queue: one batch-head pair at a time (query blocks 7..4 then 3..0 of its four map/V-half combinations) so that concurrent units read the same K/V tiles
# baseline (speedup 1.0000x reference)
.Lfq_got:
	s_bfe_u32 s92, s10, 0x10004
	s_lshl_b32 s92, s92, 2
	s_bfe_u32 s93, s10, 0x20002
	s_add_i32 s92, s92, s93
	s_lshl_b32 s92, s92, 7
	s_lshr_b32 s93, s10, 5
	s_lshl_b32 s97, s97, 2
	s_add_i32 s93, s93, s97
	s_lshl_b32 s93, s93, 2
	s_and_b32 s10, s10, 3
	s_or_b32 s10, s10, s93
	s_or_b32 s10, s10, s92
	s_branch .Lfq_done
